# scan reducer wave: all 16 LDS reads issued up front with counted waits (one LDS round trip instead of four)
# baseline (speedup 1.0000x reference)
; __device__ __forceinline__ unsigned f2bf(float f) { unsigned u = __builtin_bit_cast(unsigned, f); return (u + 0x7fffu + ((u >> 16) & 1u)) >> 16; }
; template <int MODE>
; __device__ __forceinline__ void rwkv_scan_unit(int wid_s, const bf16* SIbh_, bf16* Yb_, int ystride, int quarter, float* ldsf) {
;     ...
;             if (ch > 0) {
;                 const int s = lane >> 2, rr = lane & 3;
; #pragma unroll
;                 for (int mw = 0; mw < 4; ++mw) {
;                     const float* src = PYb + ((ch - 1) & 1) * (16 * 260) + s * 260 + mw * 64 + rr * 16;
;                     const f32x4 a = *(const f32x4*)src, b = *(const f32x4*)(src + 4), c = *(const f32x4*)(src + 8), d = *(const f32x4*)(src + 12);
;                     const float y = ((a.x + a.y) + (a.z + a.w)) + ((b.x + b.y) + (b.z + b.w)) + ((c.x + c.y) + (c.z + c.w)) + ((d.x + d.y) + (d.z + d.w));
;                     Yb[(size_t)((ch - 1) * 16 + s) * ystride + quarter * 16 + mw * 4 + rr] = (bf16)f2bf(y);
;                 }
;             }
.Lmy_cv_done:
.LBB0_1408:
	s_andn2_saveexec_b64 s[10:11], s[10:11]
	s_cbranch_execz .LBB0_1411
	s_cmp_eq_u32 s6, 0
	s_cbranch_scc1 .LBB0_1411
	s_bitcmp1_b32 s0, 0
	s_cselect_b32 s12, 0, 0x4100
	v_add_u32_e32 v63, s12, v59
	ds_read_b128 v[0:3], v63
	ds_read_b128 v[4:7], v63 offset:16
	ds_read_b128 v[8:11], v63 offset:32
	ds_read_b128 v[12:15], v63 offset:48
	ds_read_b128 v[16:19], v63 offset:256
	ds_read_b128 v[20:23], v63 offset:272
	ds_read_b128 v[24:27], v63 offset:288
	ds_read_b128 v[28:31], v63 offset:304
	ds_read_b128 v[32:35], v63 offset:512
	ds_read_b128 v[36:39], v63 offset:528
	ds_read_b128 v[40:43], v63 offset:544
	ds_read_b128 v[44:47], v63 offset:560
	ds_read_b128 v[64:67], v63 offset:768
	ds_read_b128 v[68:71], v63 offset:784
	ds_read_b128 v[72:75], v63 offset:800
	ds_read_b128 v[76:79], v63 offset:816
	s_movk_i32 s12, 0xc00
	v_mad_u64_u32 v[80:81], s[12:13], v62, s12, v[48:49]
	s_waitcnt lgkmcnt(15)
	v_add_f32_e32 v0, v0, v1
	v_add_f32_e32 v1, v2, v3
	v_add_f32_e32 v0, v0, v1
	s_waitcnt lgkmcnt(14)
	v_add_f32_e32 v1, v4, v5
	v_add_f32_e32 v2, v6, v7
	v_add_f32_e32 v1, v1, v2
	v_add_f32_e32 v0, v0, v1
	s_waitcnt lgkmcnt(13)
	v_add_f32_e32 v1, v8, v9
	v_add_f32_e32 v2, v10, v11
	v_add_f32_e32 v1, v1, v2
	v_add_f32_e32 v0, v0, v1
	s_waitcnt lgkmcnt(12)
	v_add_f32_e32 v1, v12, v13
	v_add_f32_e32 v2, v14, v15
	v_add_f32_e32 v1, v1, v2
	v_add_f32_e32 v0, v0, v1
	v_bfe_u32 v1, v0, 16, 1
	v_add3_u32 v0, v0, v1, s1
	global_store_short_d16_hi v[80:81], v0, off
	s_waitcnt lgkmcnt(11)
	v_add_f32_e32 v16, v16, v17
	v_add_f32_e32 v17, v18, v19
	v_add_f32_e32 v16, v16, v17
	s_waitcnt lgkmcnt(10)
	v_add_f32_e32 v17, v20, v21
	v_add_f32_e32 v18, v22, v23
	v_add_f32_e32 v17, v17, v18
	v_add_f32_e32 v16, v16, v17
	s_waitcnt lgkmcnt(9)
	v_add_f32_e32 v17, v24, v25
	v_add_f32_e32 v18, v26, v27
	v_add_f32_e32 v17, v17, v18
	v_add_f32_e32 v16, v16, v17
	s_waitcnt lgkmcnt(8)
	v_add_f32_e32 v17, v28, v29
	v_add_f32_e32 v18, v30, v31
	v_add_f32_e32 v17, v17, v18
	v_add_f32_e32 v16, v16, v17
	v_bfe_u32 v17, v16, 16, 1
	v_add3_u32 v16, v16, v17, s1
	global_store_short_d16_hi v[80:81], v16, off offset:8
	s_waitcnt lgkmcnt(7)
	v_add_f32_e32 v32, v32, v33
	v_add_f32_e32 v33, v34, v35
	v_add_f32_e32 v32, v32, v33
	s_waitcnt lgkmcnt(6)
	v_add_f32_e32 v33, v36, v37
	v_add_f32_e32 v34, v38, v39
	v_add_f32_e32 v33, v33, v34
	v_add_f32_e32 v32, v32, v33
	s_waitcnt lgkmcnt(5)
	v_add_f32_e32 v33, v40, v41
	v_add_f32_e32 v34, v42, v43
	v_add_f32_e32 v33, v33, v34
	v_add_f32_e32 v32, v32, v33
	s_waitcnt lgkmcnt(4)
	v_add_f32_e32 v33, v44, v45
	v_add_f32_e32 v34, v46, v47
	v_add_f32_e32 v33, v33, v34
	v_add_f32_e32 v32, v32, v33
	v_bfe_u32 v33, v32, 16, 1
	v_add3_u32 v32, v32, v33, s1
	global_store_short_d16_hi v[80:81], v32, off offset:16
	s_waitcnt lgkmcnt(3)
	v_add_f32_e32 v64, v64, v65
	v_add_f32_e32 v65, v66, v67
	v_add_f32_e32 v64, v64, v65
	s_waitcnt lgkmcnt(2)
	v_add_f32_e32 v65, v68, v69
	v_add_f32_e32 v66, v70, v71
	v_add_f32_e32 v65, v65, v66
	v_add_f32_e32 v64, v64, v65
	s_waitcnt lgkmcnt(1)
	v_add_f32_e32 v65, v72, v73
	v_add_f32_e32 v66, v74, v75
	v_add_f32_e32 v65, v65, v66
	v_add_f32_e32 v64, v64, v65
	s_waitcnt lgkmcnt(0)
	v_add_f32_e32 v65, v76, v77
	v_add_f32_e32 v66, v78, v79
	v_add_f32_e32 v65, v65, v66
	v_add_f32_e32 v64, v64, v65
	v_bfe_u32 v65, v64, 16, 1
	v_add3_u32 v64, v64, v65, s1
	global_store_short_d16_hi v[80:81], v64, off offset:24
